# attention unit epilogue: O tile staged through the idle K/V LDS region and stored row-major with 8 dwordx4 stores per lane instead of 64 two-byte stores
# speedup vs baseline: 1.0047x; 1.0047x over previous
.LBB0_557:
	s_or_b64 exec, exec, s[4:5]
	s_waitcnt lgkmcnt(0)
	s_barrier
	v_and_b32_e32 v129, 63, v181
	v_lshrrev_b32_e32 v130, 6, v181
	v_lshrrev_b32_e32 v131, 5, v129
	v_and_b32_e32 v132, 31, v129
	v_lshlrev_b32_e32 v128, 13, v130
	v_lshl_add_u32 v128, v131, 10, v128
	v_lshl_add_u32 v128, v132, 1, v128
	v_add_u32_e32 v72, v169, v176
	ds_read_b128 v[64:67], v72
	ds_read_b128 v[68:71], v72 offset:32
	s_lshl_b32 s44, s11, 1
	v_lshlrev_b32_e32 v176, 1, v168
	s_add_i32 s9, s9, s8
	s_waitcnt lgkmcnt(1)
	v_rcp_f32_e32 v73, v64
	v_rcp_f32_e32 v74, v65
	v_rcp_f32_e32 v75, v66
	v_rcp_f32_e32 v76, v67
	ds_read_b128 v[64:67], v72 offset:64
	s_waitcnt lgkmcnt(1)
	v_rcp_f32_e32 v77, v68
	v_rcp_f32_e32 v78, v69
	v_rcp_f32_e32 v79, v70
	v_rcp_f32_e32 v80, v71
	ds_read_b128 v[68:71], v72 offset:96
	s_waitcnt lgkmcnt(1)
	v_rcp_f32_e32 v72, v64
	v_rcp_f32_e32 v81, v65
	v_mov_b64_e32 v[64:65], s[60:61]
	v_mad_i64_i32 v[64:65], s[2:3], v170, s87, v[64:65]
	v_lshl_add_u64 v[64:65], v[64:65], 0, s[44:45]
	v_lshl_add_u64 v[64:65], v[64:65], 0, v[176:177]
	v_mul_u32_u24_e32 v176, 0x3000, v159
	v_mul_f32_e32 v0, v0, v73
	v_lshl_add_u64 v[64:65], v[64:65], 0, v[176:177]
	v_cvt_pk_bf16_f32 v0, v0, v177
	ds_write_b16 v128, v0
	v_mul_f32_e32 v0, v32, v73
	v_cvt_pk_bf16_f32 v0, v0, v177
	ds_write_b16 v128, v0 offset:64
	v_mul_f32_e32 v0, v16, v73
	v_cvt_pk_bf16_f32 v0, v0, v177
	ds_write_b16 v128, v0 offset:128
	v_mul_f32_e32 v0, v48, v73
	v_cvt_pk_bf16_f32 v0, v0, v177
	ds_write_b16 v128, v0 offset:192
	v_mul_f32_e32 v0, v1, v74
	v_cvt_pk_bf16_f32 v0, v0, v177
	ds_write_b16 v128, v0 offset:256
	v_mul_f32_e32 v0, v33, v74
	v_cvt_pk_bf16_f32 v0, v0, v177
	ds_write_b16 v128, v0 offset:320
	v_mul_f32_e32 v0, v17, v74
	v_cvt_pk_bf16_f32 v0, v0, v177
	ds_write_b16 v128, v0 offset:384
	v_mul_f32_e32 v0, v49, v74
	v_cvt_pk_bf16_f32 v0, v0, v177
	ds_write_b16 v128, v0 offset:448
	v_mul_f32_e32 v0, v2, v75
	s_movk_i32 s2, 0x1000
	v_cvt_pk_bf16_f32 v2, v0, v177
	v_add_co_u32_e32 v0, vcc, s2, v64
	s_movk_i32 s2, 0x2000
	s_nop 0
	v_addc_co_u32_e32 v1, vcc, 0, v65, vcc
	ds_write_b16 v128, v2 offset:512
	v_mul_f32_e32 v2, v34, v75
	v_cvt_pk_bf16_f32 v2, v2, v177
	ds_write_b16 v128, v2 offset:576
	v_mul_f32_e32 v2, v18, v75
	v_cvt_pk_bf16_f32 v2, v2, v177
	ds_write_b16 v128, v2 offset:640
	v_mul_f32_e32 v2, v50, v75
	v_cvt_pk_bf16_f32 v2, v2, v177
	ds_write_b16 v128, v2 offset:704
	v_mul_f32_e32 v0, v3, v76
	v_cvt_pk_bf16_f32 v2, v0, v177
	v_add_co_u32_e32 v0, vcc, s2, v64
	s_movk_i32 s2, 0x6000
	s_nop 0
	v_addc_co_u32_e32 v1, vcc, 0, v65, vcc
	ds_write_b16 v128, v2 offset:768
	v_mul_f32_e32 v2, v35, v76
	v_cvt_pk_bf16_f32 v2, v2, v177
	ds_write_b16 v128, v2 offset:832
	v_mul_f32_e32 v2, v19, v76
	v_cvt_pk_bf16_f32 v2, v2, v177
	ds_write_b16 v128, v2 offset:896
	v_mul_f32_e32 v2, v51, v76
	v_cvt_pk_bf16_f32 v2, v2, v177
	ds_write_b16 v128, v2 offset:960
	v_mul_f32_e32 v0, v4, v77
	v_cvt_pk_bf16_f32 v2, v0, v177
	v_add_co_u32_e32 v0, vcc, s2, v64
	s_movk_i32 s2, 0x7000
	s_nop 0
	v_addc_co_u32_e32 v1, vcc, 0, v65, vcc
	ds_write_b16 v128, v2 offset:2048
	v_mul_f32_e32 v2, v36, v77
	v_cvt_pk_bf16_f32 v2, v2, v177
	ds_write_b16 v128, v2 offset:2112
	v_mul_f32_e32 v2, v20, v77
	v_cvt_pk_bf16_f32 v2, v2, v177
	ds_write_b16 v128, v2 offset:2176
	v_mul_f32_e32 v2, v52, v77
	v_cvt_pk_bf16_f32 v2, v2, v177
	ds_write_b16 v128, v2 offset:2240
	v_mul_f32_e32 v2, v5, v78
	v_cvt_pk_bf16_f32 v2, v2, v177
	ds_write_b16 v128, v2 offset:2304
	v_mul_f32_e32 v2, v37, v78
	v_cvt_pk_bf16_f32 v2, v2, v177
	ds_write_b16 v128, v2 offset:2368
	v_mul_f32_e32 v2, v21, v78
	v_cvt_pk_bf16_f32 v2, v2, v177
	ds_write_b16 v128, v2 offset:2432
	v_mul_f32_e32 v2, v53, v78
	v_cvt_pk_bf16_f32 v2, v2, v177
	ds_write_b16 v128, v2 offset:2496
	v_mul_f32_e32 v0, v6, v79
	v_cvt_pk_bf16_f32 v2, v0, v177
	v_add_co_u32_e32 v0, vcc, s2, v64
	s_mov_b32 s2, 0xc000
	s_nop 0
	v_addc_co_u32_e32 v1, vcc, 0, v65, vcc
	ds_write_b16 v128, v2 offset:2560
	v_mul_f32_e32 v2, v38, v79
	v_cvt_pk_bf16_f32 v2, v2, v177
	ds_write_b16 v128, v2 offset:2624
	v_mul_f32_e32 v2, v22, v79
	v_cvt_pk_bf16_f32 v2, v2, v177
	ds_write_b16 v128, v2 offset:2688
	v_mul_f32_e32 v2, v54, v79
	v_cvt_pk_bf16_f32 v2, v2, v177
	ds_write_b16 v128, v2 offset:2752
	v_mul_f32_e32 v0, v7, v80
	v_cvt_pk_bf16_f32 v2, v0, v177
	v_add_co_u32_e32 v0, vcc, s84, v64
	v_rcp_f32_e32 v66, v66
	s_nop 0
	v_addc_co_u32_e32 v1, vcc, 0, v65, vcc
	ds_write_b16 v128, v2 offset:2816
	v_mul_f32_e32 v2, v39, v80
	v_cvt_pk_bf16_f32 v2, v2, v177
	ds_write_b16 v128, v2 offset:2880
	v_mul_f32_e32 v2, v23, v80
	v_cvt_pk_bf16_f32 v2, v2, v177
	ds_write_b16 v128, v2 offset:2944
	v_mul_f32_e32 v2, v55, v80
	v_cvt_pk_bf16_f32 v2, v2, v177
	ds_write_b16 v128, v2 offset:3008
	v_mul_f32_e32 v0, v8, v72
	v_cvt_pk_bf16_f32 v2, v0, v177
	v_add_co_u32_e32 v0, vcc, s2, v64
	s_mov_b32 s2, 0xd000
	s_nop 0
	v_addc_co_u32_e32 v1, vcc, 0, v65, vcc
	ds_write_b16 v128, v2 offset:4096
	v_mul_f32_e32 v2, v40, v72
	v_cvt_pk_bf16_f32 v2, v2, v177
	ds_write_b16 v128, v2 offset:4160
	v_mul_f32_e32 v2, v24, v72
	v_cvt_pk_bf16_f32 v2, v2, v177
	ds_write_b16 v128, v2 offset:4224
	v_mul_f32_e32 v2, v56, v72
	v_cvt_pk_bf16_f32 v2, v2, v177
	ds_write_b16 v128, v2 offset:4288
	v_mul_f32_e32 v2, v9, v81
	v_cvt_pk_bf16_f32 v2, v2, v177
	ds_write_b16 v128, v2 offset:4352
	v_mul_f32_e32 v2, v41, v81
	v_cvt_pk_bf16_f32 v2, v2, v177
	ds_write_b16 v128, v2 offset:4416
	v_mul_f32_e32 v2, v25, v81
	v_cvt_pk_bf16_f32 v2, v2, v177
	ds_write_b16 v128, v2 offset:4480
	v_mul_f32_e32 v2, v57, v81
	v_cvt_pk_bf16_f32 v2, v2, v177
	ds_write_b16 v128, v2 offset:4544
	v_mul_f32_e32 v0, v10, v66
	v_cvt_pk_bf16_f32 v2, v0, v177
	v_add_co_u32_e32 v0, vcc, s2, v64
	v_rcp_f32_e32 v67, v67
	s_nop 0
	v_addc_co_u32_e32 v1, vcc, 0, v65, vcc
	ds_write_b16 v128, v2 offset:4608
	v_mul_f32_e32 v2, v42, v66
	v_cvt_pk_bf16_f32 v2, v2, v177
	ds_write_b16 v128, v2 offset:4672
	v_mul_f32_e32 v2, v26, v66
	v_cvt_pk_bf16_f32 v2, v2, v177
	ds_write_b16 v128, v2 offset:4736
	v_mul_f32_e32 v2, v58, v66
	v_cvt_pk_bf16_f32 v2, v2, v177
	ds_write_b16 v128, v2 offset:4800
	v_mul_f32_e32 v0, v11, v67
	s_mov_b32 s2, 0xe000
	v_cvt_pk_bf16_f32 v2, v0, v177
	v_add_co_u32_e32 v0, vcc, s2, v64
	s_waitcnt lgkmcnt(0)
	v_rcp_f32_e32 v68, v68
	v_addc_co_u32_e32 v1, vcc, 0, v65, vcc
	ds_write_b16 v128, v2 offset:4864
	v_mul_f32_e32 v2, v43, v67
	v_cvt_pk_bf16_f32 v2, v2, v177
	ds_write_b16 v128, v2 offset:4928
	v_mul_f32_e32 v2, v27, v67
	v_cvt_pk_bf16_f32 v2, v2, v177
	ds_write_b16 v128, v2 offset:4992
	v_mul_f32_e32 v2, v59, v67
	v_cvt_pk_bf16_f32 v2, v2, v177
	ds_write_b16 v128, v2 offset:5056
	v_mul_f32_e32 v0, v12, v68
	s_mov_b32 s2, 0x12000
	v_cvt_pk_bf16_f32 v2, v0, v177
	v_add_co_u32_e32 v0, vcc, s2, v64
	v_rcp_f32_e32 v69, v69
	s_nop 0
	v_addc_co_u32_e32 v1, vcc, 0, v65, vcc
	ds_write_b16 v128, v2 offset:6144
	v_mul_f32_e32 v2, v44, v68
	v_cvt_pk_bf16_f32 v2, v2, v177
	ds_write_b16 v128, v2 offset:6208
	v_mul_f32_e32 v2, v28, v68
	v_cvt_pk_bf16_f32 v2, v2, v177
	ds_write_b16 v128, v2 offset:6272
	v_mul_f32_e32 v2, v60, v68
	v_cvt_pk_bf16_f32 v2, v2, v177
	ds_write_b16 v128, v2 offset:6336
	v_mul_f32_e32 v2, v13, v69
	v_cvt_pk_bf16_f32 v2, v2, v177
	ds_write_b16 v128, v2 offset:6400
	v_mul_f32_e32 v2, v45, v69
	v_rcp_f32_e32 v70, v70
	v_cvt_pk_bf16_f32 v2, v2, v177
	ds_write_b16 v128, v2 offset:6464
	v_mul_f32_e32 v2, v29, v69
	v_cvt_pk_bf16_f32 v2, v2, v177
	ds_write_b16 v128, v2 offset:6528
	v_mul_f32_e32 v2, v61, v69
	v_cvt_pk_bf16_f32 v2, v2, v177
	ds_write_b16 v128, v2 offset:6592
	v_mul_f32_e32 v0, v14, v70
	s_mov_b32 s2, 0x13000
	v_cvt_pk_bf16_f32 v2, v0, v177
	v_add_co_u32_e32 v0, vcc, s2, v64
	v_rcp_f32_e32 v71, v71
	s_nop 0
	v_addc_co_u32_e32 v1, vcc, 0, v65, vcc
	ds_write_b16 v128, v2 offset:6656
	v_mul_f32_e32 v2, v46, v70
	v_cvt_pk_bf16_f32 v2, v2, v177
	ds_write_b16 v128, v2 offset:6720
	v_mul_f32_e32 v2, v30, v70
	v_cvt_pk_bf16_f32 v2, v2, v177
	ds_write_b16 v128, v2 offset:6784
	v_mul_f32_e32 v2, v62, v70
	v_cvt_pk_bf16_f32 v2, v2, v177
	ds_write_b16 v128, v2 offset:6848
	v_mul_f32_e32 v0, v15, v71
	s_mov_b32 s2, 0x14000
	v_cvt_pk_bf16_f32 v2, v0, v177
	v_add_co_u32_e32 v0, vcc, s2, v64
	s_cmp_ge_i32 s9, s10
	s_nop 0
	v_addc_co_u32_e32 v1, vcc, 0, v65, vcc
	ds_write_b16 v128, v2 offset:6912
	v_mul_f32_e32 v2, v47, v71
	v_cvt_pk_bf16_f32 v2, v2, v177
	ds_write_b16 v128, v2 offset:6976
	v_mul_f32_e32 v2, v31, v71
	v_cvt_pk_bf16_f32 v2, v2, v177
	ds_write_b16 v128, v2 offset:7040
	v_mul_f32_e32 v2, v63, v71
	v_cvt_pk_bf16_f32 v2, v2, v177
	ds_write_b16 v128, v2 offset:7104
	v_lshrrev_b32_e32 v133, 4, v129
	v_and_b32_e32 v134, 15, v129
	v_lshlrev_b32_e32 v135, 13, v130
	v_lshl_add_u32 v135, v133, 8, v135
	v_lshl_add_u32 v135, v134, 4, v135
	s_waitcnt lgkmcnt(0)
	ds_read_b128 v[182:185], v135
	ds_read_b128 v[186:189], v135 offset:1024
	ds_read_b128 v[190:193], v135 offset:2048
	ds_read_b128 v[194:197], v135 offset:3072
	ds_read_b128 v[198:201], v135 offset:4096
	ds_read_b128 v[202:205], v135 offset:5120
	ds_read_b128 v[206:209], v135 offset:6144
	ds_read_b128 v[210:213], v135 offset:7168
	v_mul_u32_u24_e32 v136, 0x3000, v131
	v_lshl_add_u32 v136, v132, 1, v136
	v_mov_b32_e32 v137, 0
	v_sub_co_u32_e32 v64, vcc, v64, v136
	s_nop 1
	v_subb_co_u32_e32 v65, vcc, v65, v137, vcc
	v_mul_u32_u24_e32 v136, 0xc00, v133
	v_lshl_add_u32 v136, v134, 4, v136
	v_lshl_add_u64 v[64:65], v[64:65], 0, v[136:137]
	s_mov_b64 s[6:7], 0x3000
	s_waitcnt lgkmcnt(7)
	global_store_dwordx4 v[64:65], v[182:185], off
	v_lshl_add_u64 v[64:65], v[64:65], 0, s[6:7]
	s_waitcnt lgkmcnt(6)
	global_store_dwordx4 v[64:65], v[186:189], off
	v_lshl_add_u64 v[64:65], v[64:65], 0, s[6:7]
	s_waitcnt lgkmcnt(5)
	global_store_dwordx4 v[64:65], v[190:193], off
	v_lshl_add_u64 v[64:65], v[64:65], 0, s[6:7]
	s_waitcnt lgkmcnt(4)
	global_store_dwordx4 v[64:65], v[194:197], off
	v_lshl_add_u64 v[64:65], v[64:65], 0, s[6:7]
	s_waitcnt lgkmcnt(3)
	global_store_dwordx4 v[64:65], v[198:201], off
	v_lshl_add_u64 v[64:65], v[64:65], 0, s[6:7]
	s_waitcnt lgkmcnt(2)
	global_store_dwordx4 v[64:65], v[202:205], off
	v_lshl_add_u64 v[64:65], v[64:65], 0, s[6:7]
	s_waitcnt lgkmcnt(1)
	global_store_dwordx4 v[64:65], v[206:209], off
	v_lshl_add_u64 v[64:65], v[64:65], 0, s[6:7]
	s_waitcnt lgkmcnt(0)
	global_store_dwordx4 v[64:65], v[210:213], off
	s_waitcnt vmcnt(63) expcnt(7) lgkmcnt(15)
	s_barrier
	s_cbranch_scc1 .LBB0_579
